# RWKV: producer-wave priority raise removed (scan waves are the critical path now)
# speedup vs baseline: 1.0039x; 1.0013x over previous
.LBB0_572:
	s_andn2_saveexec_b64 s[0:1], s[6:7]
	v_or_b32_e32 v40, 1, v84
	v_or_b32_e32 v41, 2, v84
	v_or_b32_e32 v42, 3, v84
	v_or_b32_e32 v85, v37, v76
	v_lshl_or_b32 v86, v40, 6, v76
	v_lshl_or_b32 v87, v41, 6, v76
	v_lshl_or_b32 v88, v42, 6, v76
	s_or_b64 exec, exec, s[0:1]
	s_movk_i32 s0, 0xc0
	v_and_or_b32 v90, v30, s0, v37
	v_or_b32_e32 v37, v84, v29
	v_or_b32_e32 v30, 16, v39
	v_mul_u32_u24_e32 v93, 0x44, v37
	v_readlane_b32 s16, v253, 18
	v_readlane_b32 s1, v253, 17
	v_lshlrev_b32_e32 v43, 5, v30
	v_lshl_add_u32 v44, v93, 2, s16
	v_add_u32_e32 v92, s1, v43
	v_add3_u32 v94, v44, v43, s94
	v_lshlrev_b32_e32 v95, 6, v37
	v_or_b32_e32 v37, 32, v39
	s_ashr_i32 s3, s2, 31
	v_and_b32_e32 v43, 56, v83
	v_lshl_add_u32 v89, v39, 5, s1
	v_lshlrev_b32_e32 v91, 3, v30
	v_lshl_add_u32 v96, v37, 5, s1
	s_lshl_b64 s[0:1], s[2:3], 11
	v_or_b32_e32 v44, s24, v43
	v_lshrrev_b32_e32 v28, 2, v28
	v_lshl_or_b32 v36, v77, 6, v36
	v_or_b32_e32 v52, s0, v84
	v_or_b32_e32 v44, 0x900, v44
	v_add_u32_e32 v45, 0x940, v91
	v_cmp_gt_u32_e32 vcc, 24, v30
	s_add_i32 s0, s24, 0x940
	v_and_b32_e32 v98, 62, v28
	v_add_lshl_u32 v28, v2, v35, 2
	v_lshl_or_b32 v35, v35, 8, v36
	v_readlane_b32 s17, v253, 19
	v_cmp_lt_u32_e64 s[8:9], 23, v30
	v_mov_b32_e32 v53, s1
	v_cndmask_b32_e32 v30, v45, v44, vcc
	v_mov_b32_e32 v44, s0
	v_add_u32_e32 v100, s16, v28
	s_add_i32 s0, 0, 0x10100
	v_add_u32_e32 v102, s17, v28
	s_add_i32 s1, 0, 0x14100
	v_or_b32_e32 v28, 0x100, v35
	v_add_u32_e32 v104, s0, v28
	v_add_u32_e32 v105, s1, v28
	v_or_b32_e32 v28, 0x200, v35
	v_add_u32_e32 v107, s0, v28
	v_add_u32_e32 v108, s1, v28
	v_or_b32_e32 v28, 0x300, v35
	v_add_u32_e32 v109, s0, v28
	v_add_u32_e32 v110, s1, v28
	v_add_lshl_u32 v28, v34, v2, 2
	v_add_u32_e32 v111, s16, v28
	v_add_u32_e32 v113, s17, v28
	v_or_b32_e32 v28, 0x500, v35
	v_add_u32_e32 v115, s0, v28
	v_add_u32_e32 v116, s1, v28
	v_or_b32_e32 v28, 0x600, v35
	v_add_u32_e32 v117, s0, v28
	v_add_u32_e32 v118, s1, v28
	v_or_b32_e32 v28, 0x700, v35
	v_add_u32_e32 v119, s0, v28
	v_add_u32_e32 v120, s1, v28
	v_add_lshl_u32 v28, v33, v2, 2
	v_add_u32_e32 v121, s16, v28
	v_add_u32_e32 v123, s17, v28
	v_or_b32_e32 v28, 0x900, v35
	v_add_u32_e32 v125, s0, v28
	v_add_u32_e32 v126, s1, v28
	v_or_b32_e32 v28, 0xa00, v35
	v_add_u32_e32 v127, s0, v28
	v_add_u32_e32 v128, s1, v28
	v_or_b32_e32 v28, 0xb00, v35
	v_add_u32_e32 v129, s0, v28
	v_add_u32_e32 v130, s1, v28
	v_add_lshl_u32 v28, v32, v2, 2
	v_add_u32_e32 v131, s16, v28
	v_add_u32_e32 v133, s17, v28
	v_or_b32_e32 v28, 0xd00, v35
	v_lshl_or_b32 v34, v34, 8, v36
	v_lshl_or_b32 v33, v33, 8, v36
	v_lshl_or_b32 v32, v32, 8, v36
	v_add_u32_e32 v135, s0, v28
	v_add_u32_e32 v136, s1, v28
	v_or_b32_e32 v28, 0xe00, v35
	v_add_lshl_u32 v2, v3, v2, 2
	v_lshl_or_b32 v3, v3, 8, v36
	v_add_u32_e32 v101, s0, v35
	v_add_u32_e32 v112, s0, v34
	v_add_u32_e32 v122, s0, v33
	v_add_u32_e32 v132, s0, v32
	v_add_u32_e32 v137, s0, v28
	v_add_u32_e32 v140, s0, v3
	s_add_i32 s0, 0, 0x10000
	v_and_b32_e32 v1, 0xc00, v1
	v_add_u32_e32 v103, s1, v35
	v_add_u32_e32 v114, s1, v34
	v_add_u32_e32 v124, s1, v33
	v_add_u32_e32 v134, s1, v32
	v_add_u32_e32 v138, s1, v28
	v_add_u32_e32 v139, s16, v2
	v_add_u32_e32 v141, s17, v2
	v_add_u32_e32 v142, s1, v3
	v_lshl_add_u32 v106, v84, 2, s0
	v_lshl_add_u32 v144, v40, 2, s0
	v_lshl_add_u32 v145, v41, 2, s0
	v_lshl_add_u32 v146, v42, 2, s0
	v_add3_u32 v147, 0, v36, v1
	s_mul_hi_i32 s0, s2, 0xf00000
	s_mul_i32 s1, s2, 0xf00000
	v_mul_hi_u32_u24_e32 v1, 0x7800, v77
	v_mul_u32_u24_e32 v2, 0x7800, v77
	v_or_b32_e32 v3, s0, v1
	v_or_b32_e32 v2, s1, v2
	s_movk_i32 s0, 0x1e00
	v_or_b32_e32 v1, s24, v38
	v_mad_u64_u32 v[2:3], s[0:1], v29, s0, v[2:3]
	v_add_lshl_u32 v28, v1, v43, 1
	v_mov_b32_e32 v29, v0
	v_lshl_add_u64 v[28:29], v[2:3], 0, v[28:29]
	v_cmp_gt_u32_e64 s[6:7], 8, v39
	v_cmp_lt_u32_e64 s[10:11], 39, v37
	v_lshlrev_b32_e32 v39, 3, v37
	v_cmp_gt_u32_e64 s[12:13], 40, v37
	v_mov_b32_e32 v37, 0x940
	v_lshl_add_u64 v[54:55], s[58:59], 0, v[28:29]
	v_lshlrev_b32_e32 v28, 1, v30
	v_mov_b32_e32 v29, v0
	v_cndmask_b32_e64 v37, v44, v37, s[12:13]
	v_lshl_add_u64 v[28:29], v[2:3], 0, v[28:29]
	v_lshl_add_u64 v[56:57], s[58:59], 0, v[28:29]
	v_add_u32_e32 v1, v37, v83
	v_mov_b32_e32 v28, 0x200
	v_lshl_add_u32 v28, v1, 1, v28
	v_mov_b32_e32 v29, v0
	v_lshl_add_u64 v[2:3], v[2:3], 0, v[28:29]
	v_mov_b32_e32 v1, v0
	v_lshlrev_b32_e32 v97, 3, v31
	s_mov_b32 s25, 0
	v_cmp_eq_u32_e64 s[14:15], 0, v31
	v_lshl_add_u32 v99, v98, 2, 0
	v_lshl_add_u32 v143, v31, 5, 0
	v_cmp_eq_u32_e64 s[16:17], 0, v76
	v_mov_b32_e32 v49, v48
	v_mov_b32_e32 v51, v50
	v_lshl_add_u64 v[58:59], s[58:59], 0, v[2:3]
	s_mov_b32 s88, -16
	s_mov_b64 s[18:19], 0
	v_lshlrev_b32_e32 v148, 2, v39
	v_mov_b64_e32 v[44:45], v[0:1]
	v_mov_b64_e32 v[46:47], v[0:1]
	v_mov_b64_e32 v[60:61], v[0:1]
	v_mov_b64_e32 v[62:63], v[0:1]
	v_mov_b64_e32 v[64:65], v[0:1]
	v_mov_b64_e32 v[66:67], v[0:1]
	v_mov_b64_e32 v[68:69], v[0:1]
	v_mov_b64_e32 v[70:71], v[0:1]
	s_waitcnt lgkmcnt(0)
	s_barrier
	s_cmp_eq_u64 s[4:5], 0
	s_cbranch_scc1 .Lrw_prio_skip
	s_setprio 0
